# v29 + diff attention: accumulator-offset (NEGM) zero-init hoisted to the tile-loop preheader, removing a taken wave-uniform branch at the head of every tile body (loop-edge edit)
# baseline (speedup 1.0000x reference)
; template <int DQ, bool NA, int NQG>
; DI void attn_wg(const half_t* Qp, const half_t* Kp, const half_t* Vp, int q0, bool active, int seg0_start, int seg0_tiles,
;                 int seg1_start, int seg1_tiles, const float* rpb_h, int rq, char* smem, int tid, f16v (&O)[2][NQG]) {
;     ...
;   float mrun[NQG], lrun[NQG];
; #pragma unroll
;   for (int qg = 0; qg < NQG; ++qg) { mrun[qg] = -1e30f; lrun[qg] = 0.f; }
; #pragma unroll
;   for (int a = 0; a < 2; ++a)
; #pragma unroll
;     for (int c = 0; c < NQG; ++c)
; #pragma unroll
;       for (int i = 0; i < 16; ++i) O[a][c][i] = 0.f;
;   const int ntiles = seg0_tiles + seg1_tiles;
;   const int kc0 = tid, kc1 = tid + 512;
;   const half_t* kg0 = Kp + kc0 * 8;
;   const half_t* kg1 = Kp + kc1 * 8;
;   const half_t* vg = Vp + (size_t)(tid >> 3) * TOK + (tid & 7) * 8;
;   const int ks0 = (kc0 / CPK) * KSTR + (kc0 % CPK) * 8, ks1 = (kc1 / CPK) * KSTR + (kc1 % CPK) * 8, vs0 = (tid >> 3) * VSTR + (tid & 7) * 8;
;   uint4 kreg0 = {0, 0, 0, 0}, kreg1 = {0, 0, 0, 0}, vreg;
;   const int r0w = min(max(rq - 4, 0), 24);
;   {
;     const int k0 = (0 < seg0_tiles) ? seg0_start : seg1_start;
;     if (kc0 < KCH) kreg0 = *(const uint4*)(kg0 + (size_t)k0 * DQ);
;     if (DQ == 96 && kc1 < KCH) kreg1 = *(const uint4*)(kg1 + (size_t)k0 * DQ);
;     vreg = *(const uint4*)(vg + k0);
;     if (kc0 < KCH) *(uint4*)((half_t*)smem + ks0) = kreg0;
;     if (DQ == 96 && kc1 < KCH) *(uint4*)((half_t*)smem + ks1) = kreg1;
;     *(uint4*)((half_t*)(smem + ATT_VOFF) + vs0) = vreg;
;   }
;   __syncthreads();
.LBB0_2034:
	s_or_b64 exec, exec, s[6:7]
	v_mov_b32_e32 v14, v0
	v_mov_b32_e32 v15, v0
	v_mov_b32_e32 v1, v0
	v_mov_b32_e32 v2, v0
	v_mov_b32_e32 v3, v0
	v_mov_b32_e32 v4, v0
	v_mov_b32_e32 v5, v0
	v_mov_b32_e32 v6, v0
	v_mov_b32_e32 v7, v0
	v_mov_b32_e32 v8, v0
	v_mov_b32_e32 v9, v0
	v_mov_b32_e32 v10, v0
	v_mov_b32_e32 v11, v0
	v_mov_b32_e32 v12, v0
	v_mov_b32_e32 v13, v0
	v_mov_b64_e32 v[30:31], v[14:15]
	v_mov_b64_e32 v[46:47], v[14:15]
	v_mov_b64_e32 v[62:63], v[14:15]
	v_mov_b64_e32 v[78:79], v[14:15]
	s_mov_b32 s18, 0
	s_waitcnt vmcnt(5)
	v_mov_b32_e32 v148, 0xf149f2ca
	v_mov_b32_e32 v149, 0
	v_mov_b64_e32 v[28:29], v[12:13]
	v_mov_b64_e32 v[26:27], v[10:11]
	v_mov_b64_e32 v[24:25], v[8:9]
	v_mov_b64_e32 v[22:23], v[6:7]
	v_mov_b64_e32 v[20:21], v[4:5]
	v_mov_b64_e32 v[18:19], v[2:3]
	v_mov_b64_e32 v[16:17], v[0:1]
	v_mov_b64_e32 v[44:45], v[12:13]
	v_mov_b64_e32 v[42:43], v[10:11]
	v_mov_b64_e32 v[40:41], v[8:9]
	v_mov_b64_e32 v[38:39], v[6:7]
	v_mov_b64_e32 v[36:37], v[4:5]
	v_mov_b64_e32 v[34:35], v[2:3]
	v_mov_b64_e32 v[32:33], v[0:1]
	v_mov_b64_e32 v[60:61], v[12:13]
	v_mov_b64_e32 v[58:59], v[10:11]
	v_mov_b64_e32 v[56:57], v[8:9]
	v_mov_b64_e32 v[54:55], v[6:7]
	v_mov_b64_e32 v[52:53], v[4:5]
	v_mov_b64_e32 v[50:51], v[2:3]
	v_mov_b64_e32 v[48:49], v[0:1]
	v_mov_b64_e32 v[76:77], v[12:13]
	v_mov_b64_e32 v[74:75], v[10:11]
	v_mov_b64_e32 v[72:73], v[8:9]
	v_mov_b64_e32 v[70:71], v[6:7]
	v_mov_b64_e32 v[68:69], v[4:5]
	v_mov_b64_e32 v[66:67], v[2:3]
	v_mov_b64_e32 v[64:65], v[0:1]
	v_mov_b32_e32 v1, 0
	v_mov_b32_e32 v14, 0xf149f2ca
	s_waitcnt vmcnt(0)
	ds_write_b128 v195, v[132:135] offset:13312
	s_waitcnt lgkmcnt(0)
	s_barrier
	v_add3_u32 v15, 0, v251, v156
	v_add3_u32 v183, 0, v239, v155
	v_add_u32_e32 v187, 0x4600, v183
	v_add_u32_e32 v183, 0x3400, v183
	v_mov_b32_e32 v196, 0
	v_mov_b32_e32 v197, 0
	v_mov_b32_e32 v198, 0
	v_mov_b32_e32 v199, 0
	v_mov_b32_e32 v200, 0
	v_mov_b32_e32 v201, 0
	v_mov_b32_e32 v202, 0
	v_mov_b32_e32 v203, 0
	v_mov_b32_e32 v204, 0
	v_mov_b32_e32 v205, 0
	v_mov_b32_e32 v206, 0
	v_mov_b32_e32 v207, 0
	v_mov_b32_e32 v208, 0
	v_mov_b32_e32 v209, 0
	v_mov_b32_e32 v210, 0
	v_mov_b32_e32 v211, 0
	v_mov_b32_e32 v212, 0
	v_mov_b32_e32 v213, 0
	v_mov_b32_e32 v214, 0
	v_mov_b32_e32 v215, 0
	v_mov_b32_e32 v216, 0
	v_mov_b32_e32 v217, 0
	v_mov_b32_e32 v218, 0
	v_mov_b32_e32 v219, 0
	v_mov_b32_e32 v220, 0
	v_mov_b32_e32 v221, 0
	v_mov_b32_e32 v222, 0
	v_mov_b32_e32 v223, 0
	v_mov_b32_e32 v224, 0
	v_mov_b32_e32 v225, 0
	v_mov_b32_e32 v226, 0
	v_mov_b32_e32 v227, 0

; template <int DQ, bool NA, int NQG>
; DI void attn_wg(const half_t* Qp, const half_t* Kp, const half_t* Vp, int q0, bool active, int seg0_start, int seg0_tiles,
;                 int seg1_start, int seg1_tiles, const float* rpb_h, int rq, char* smem, int tid, f16v (&O)[2][NQG]) {
;     ...
;     const half_t* ksm = (const half_t*)(smem + (it & 1) * ATT_STAGE) + r * KSTR + h * 8;
;     const half_t* vsm = (const half_t*)(smem + (it & 1) * ATT_STAGE + ATT_VOFF) + r * VSTR + h * 4;
;     const bool masked = NA && it < seg0_tiles;
;     const int krow = k0 >> 6;
;     const bool need = active && (!masked || (krow >= r0w && krow < r0w + 8));
;     if (need) {
; #pragma unroll 1
;       for (int st = 0; st < 2; ++st) {
;         f16v S[NQG];
; #pragma unroll
;         for (int qg = 0; qg < NQG; ++qg)
; #pragma unroll
;           for (int i = 0; i < 16; ++i) S[qg][i] = 0.f;
; #pragma unroll
;         for (int ks = 0; ks < NKS; ++ks) {
;           const h8 kf = *(const h8*)(ksm + (st * 32) * KSTR + ks * 16);
; #pragma unroll
;           for (int qg = 0; qg < NQG; ++qg) S[qg] = __builtin_amdgcn_mfma_f32_32x32x16_f16(kf, qf[qg][ks], S[qg], 0, 0, 0);
.LBB0_2039:
	v_cndmask_b32_e64 v2, 0, 1, s[14:15]
	v_cmp_ne_u32_e64 s[6:7], 1, v2
	s_andn2_b64 vcc, exec, s[14:15]
	s_cbranch_vccnz .LBB0_2046
	s_cmp_eq_u32 s18, 0
	s_cselect_b32 s19, 1, 0
	s_bitcmp1_b32 s18, 0
	s_cselect_b32 s18, 0x5800, 0
	ds_read_b128 v[2:5], v15 offset:0
	ds_read_b128 v[6:9], v15 offset:32
	ds_read2_b64 v[10:13], v183 offset0:0 offset1:2
	ds_read2_b64 v[136:139], v183 offset0:4 offset1:6
	ds_read2_b64 v[150:153], v187 offset0:0 offset1:2
	ds_read2_b64 v[190:193], v187 offset0:4 offset1:6
	s_waitcnt lgkmcnt(5)
	v_mfma_f32_32x32x16_f16 v[96:111], v[2:5], v[112:115], v[196:211]
	s_waitcnt lgkmcnt(4)
	v_mfma_f32_32x32x16_f16 v[96:111], v[6:9], v[116:119], v[96:111]
	s_cmp_lg_u32 s19, 0
	s_cbranch_scc1 .Lfirst_diff1c_0

; template <int DQ, bool NA, int NQG>
; DI void attn_wg(const half_t* Qp, const half_t* Kp, const half_t* Vp, int q0, bool active, int seg0_start, int seg0_tiles,
;                 int seg1_start, int seg1_tiles, const float* rpb_h, int rq, char* smem, int tid, f16v (&O)[2][NQG]) {
;     ...
;   float mrun[NQG], lrun[NQG];
; #pragma unroll
;   for (int qg = 0; qg < NQG; ++qg) { mrun[qg] = -1e30f; lrun[qg] = 0.f; }
; #pragma unroll
;   for (int a = 0; a < 2; ++a)
; #pragma unroll
;     for (int c = 0; c < NQG; ++c)
; #pragma unroll
;       for (int i = 0; i < 16; ++i) O[a][c][i] = 0.f;
;   const int ntiles = seg0_tiles + seg1_tiles;
;   const int kc0 = tid, kc1 = tid + 512;
;   const half_t* kg0 = Kp + kc0 * 8;
;   const half_t* kg1 = Kp + kc1 * 8;
;   const half_t* vg = Vp + (size_t)(tid >> 3) * TOK + (tid & 7) * 8;
;   const int ks0 = (kc0 / CPK) * KSTR + (kc0 % CPK) * 8, ks1 = (kc1 / CPK) * KSTR + (kc1 % CPK) * 8, vs0 = (tid >> 3) * VSTR + (tid & 7) * 8;
;   uint4 kreg0 = {0, 0, 0, 0}, kreg1 = {0, 0, 0, 0}, vreg;
;   const int r0w = min(max(rq - 4, 0), 24);
;   {
;     const int k0 = (0 < seg0_tiles) ? seg0_start : seg1_start;
;     if (kc0 < KCH) kreg0 = *(const uint4*)(kg0 + (size_t)k0 * DQ);
;     if (DQ == 96 && kc1 < KCH) kreg1 = *(const uint4*)(kg1 + (size_t)k0 * DQ);
;     vreg = *(const uint4*)(vg + k0);
;     if (kc0 < KCH) *(uint4*)((half_t*)smem + ks0) = kreg0;
;     if (DQ == 96 && kc1 < KCH) *(uint4*)((half_t*)smem + ks1) = kreg1;
;     *(uint4*)((half_t*)(smem + ATT_VOFF) + vs0) = vreg;
;   }
;   __syncthreads();
.LBB0_2056:
	s_or_b64 exec, exec, s[14:15]
	v_mov_b32_e32 v14, v0
	v_mov_b32_e32 v15, v0
	v_mov_b32_e32 v1, v0
	v_mov_b32_e32 v2, v0
	v_mov_b32_e32 v3, v0
	v_mov_b32_e32 v4, v0
	v_mov_b32_e32 v5, v0
	v_mov_b32_e32 v6, v0
	v_mov_b32_e32 v7, v0
	v_mov_b32_e32 v8, v0
	v_mov_b32_e32 v9, v0
	v_mov_b32_e32 v10, v0
	v_mov_b32_e32 v11, v0
	v_mov_b32_e32 v12, v0
	v_mov_b32_e32 v13, v0
	v_mov_b64_e32 v[30:31], v[14:15]
	v_mov_b64_e32 v[62:63], v[14:15]
	v_mov_b64_e32 v[46:47], v[14:15]
	v_mov_b64_e32 v[78:79], v[14:15]
	s_mov_b32 s19, 0
	v_mov_b32_e32 v144, 0xf149f2ca
	v_mov_b32_e32 v145, 0
	v_mov_b64_e32 v[28:29], v[12:13]
	v_mov_b64_e32 v[26:27], v[10:11]
	v_mov_b64_e32 v[24:25], v[8:9]
	v_mov_b64_e32 v[22:23], v[6:7]
	v_mov_b64_e32 v[20:21], v[4:5]
	v_mov_b64_e32 v[18:19], v[2:3]
	v_mov_b64_e32 v[16:17], v[0:1]
	v_mov_b64_e32 v[60:61], v[12:13]
	v_mov_b64_e32 v[58:59], v[10:11]
	v_mov_b64_e32 v[56:57], v[8:9]
	v_mov_b64_e32 v[54:55], v[6:7]
	v_mov_b64_e32 v[52:53], v[4:5]
	v_mov_b64_e32 v[50:51], v[2:3]
	v_mov_b64_e32 v[48:49], v[0:1]
	v_mov_b64_e32 v[44:45], v[12:13]
	v_mov_b64_e32 v[42:43], v[10:11]
	v_mov_b64_e32 v[40:41], v[8:9]
	v_mov_b64_e32 v[38:39], v[6:7]
	v_mov_b64_e32 v[36:37], v[4:5]
	v_mov_b64_e32 v[34:35], v[2:3]
	v_mov_b64_e32 v[32:33], v[0:1]
	v_mov_b64_e32 v[76:77], v[12:13]
	v_mov_b64_e32 v[74:75], v[10:11]
	v_mov_b64_e32 v[72:73], v[8:9]
	v_mov_b64_e32 v[70:71], v[6:7]
	v_mov_b64_e32 v[68:69], v[4:5]
	v_mov_b64_e32 v[66:67], v[2:3]
	v_mov_b64_e32 v[64:65], v[0:1]
	v_mov_b32_e32 v1, 0
	v_mov_b32_e32 v14, 0xf149f2ca
	s_waitcnt vmcnt(0)
	ds_write_b128 v195, v[132:135] offset:13312
	s_waitcnt lgkmcnt(0)
	s_barrier
	v_add3_u32 v15, 0, v251, v156
	v_add3_u32 v151, 0, v239, v155
	v_add_u32_e32 v152, 0x4600, v151
	v_add_u32_e32 v151, 0x3400, v151
	v_mov_b32_e32 v196, 0
	v_mov_b32_e32 v197, 0
	v_mov_b32_e32 v198, 0
	v_mov_b32_e32 v199, 0
	v_mov_b32_e32 v200, 0
	v_mov_b32_e32 v201, 0
	v_mov_b32_e32 v202, 0
	v_mov_b32_e32 v203, 0
	v_mov_b32_e32 v204, 0
	v_mov_b32_e32 v205, 0
	v_mov_b32_e32 v206, 0
	v_mov_b32_e32 v207, 0
	v_mov_b32_e32 v208, 0
	v_mov_b32_e32 v209, 0
	v_mov_b32_e32 v210, 0
	v_mov_b32_e32 v211, 0
	v_mov_b32_e32 v212, 0
	v_mov_b32_e32 v213, 0
	v_mov_b32_e32 v214, 0
	v_mov_b32_e32 v215, 0
	v_mov_b32_e32 v216, 0
	v_mov_b32_e32 v217, 0
	v_mov_b32_e32 v218, 0
	v_mov_b32_e32 v219, 0
	v_mov_b32_e32 v220, 0
	v_mov_b32_e32 v221, 0
	v_mov_b32_e32 v222, 0
	v_mov_b32_e32 v223, 0
	v_mov_b32_e32 v224, 0
	v_mov_b32_e32 v225, 0
	v_mov_b32_e32 v226, 0
	v_mov_b32_e32 v227, 0

; template <int DQ, bool NA, int NQG>
; DI void attn_wg(const half_t* Qp, const half_t* Kp, const half_t* Vp, int q0, bool active, int seg0_start, int seg0_tiles,
;                 int seg1_start, int seg1_tiles, const float* rpb_h, int rq, char* smem, int tid, f16v (&O)[2][NQG]) {
;     ...
;     const half_t* ksm = (const half_t*)(smem + (it & 1) * ATT_STAGE) + r * KSTR + h * 8;
;     const half_t* vsm = (const half_t*)(smem + (it & 1) * ATT_STAGE + ATT_VOFF) + r * VSTR + h * 4;
;     const bool masked = NA && it < seg0_tiles;
;     const int krow = k0 >> 6;
;     const bool need = active && (!masked || (krow >= r0w && krow < r0w + 8));
;     if (need) {
; #pragma unroll 1
;       for (int st = 0; st < 2; ++st) {
;         f16v S[NQG];
; #pragma unroll
;         for (int qg = 0; qg < NQG; ++qg)
; #pragma unroll
;           for (int i = 0; i < 16; ++i) S[qg][i] = 0.f;
; #pragma unroll
;         for (int ks = 0; ks < NKS; ++ks) {
;           const h8 kf = *(const h8*)(ksm + (st * 32) * KSTR + ks * 16);
; #pragma unroll
;           for (int qg = 0; qg < NQG; ++qg) S[qg] = __builtin_amdgcn_mfma_f32_32x32x16_f16(kf, qf[qg][ks], S[qg], 0, 0, 0);
.LBB0_2061:
	s_and_b64 vcc, exec, s[6:7]
	s_cbranch_vccnz .LBB0_2068
	s_cmp_eq_u32 s19, 0
	s_cselect_b32 s17, 1, 0
	s_bitcmp1_b32 s19, 0
	s_cselect_b32 s16, 0x5800, 0
	ds_read_b128 v[2:5], v15 offset:0
	ds_read_b128 v[6:9], v15 offset:32
	ds_read2_b64 v[10:13], v151 offset0:0 offset1:2
	ds_read2_b64 v[136:139], v151 offset0:4 offset1:6
	ds_read2_b64 v[146:149], v152 offset0:0 offset1:2
	ds_read2_b64 v[190:193], v152 offset0:4 offset1:6
	s_waitcnt lgkmcnt(5)
	v_mfma_f32_32x32x16_f16 v[96:111], v[2:5], v[112:115], v[196:211]
	s_waitcnt lgkmcnt(4)
	v_mfma_f32_32x32x16_f16 v[96:111], v[6:9], v[116:119], v[96:111]
	s_cmp_lg_u32 s17, 0
	s_cbranch_scc1 .Lfirst_diff2c_0
